# FF1 epilogue: nt hint on the H output stores (streaming, keep operands in L2/MALL)
# speedup vs baseline: 1.0100x; 1.0056x over previous
; __device__ __forceinline__ unsigned cvt_pk_bf16(float lo, float hi) { unsigned r; asm volatile("v_cvt_pk_bf16_f32 %0, %1, %2" : "=v"(r) : "v"(lo), "v"(hi)); return r; }
;     __device__ __forceinline__ void operator()(const f32x4 (&acc)[2][2][4][2], const Unit& u, int wr, int wc, int fr, int fq) const {
;         const int row0 = u.pm * BM + wr * 64 + fr, col0 = u.pn * BM + wc * 32 + 8 * fq;
; #pragma unroll
;         for (int ai = 0; ai < 2; ++ai)
; #pragma unroll
;             for (int m = 0; m < 4; ++m) {
;                 const int rowi = row0 + ai * HALF + m * 16;
; #pragma unroll
;                 for (int bj = 0; bj < 2; ++bj) {
;                     f32x4 v0 = acc[ai][bj][m][0], v1 = acc[ai][bj][m][1];
; #pragma unroll
;                     for (int j = 0; j < 4; ++j) { const float a = fmaxf(v0[j], 0.f), b = fmaxf(v1[j], 0.f); v0[j] = a * a; v1[j] = b * b; }
;                     u32x4 w; w.x = cvt_pk_bf16(v0[0], v0[1]); w.y = cvt_pk_bf16(v0[2], v0[3]); w.z = cvt_pk_bf16(v1[0], v1[1]); w.w = cvt_pk_bf16(v1[2], v1[3]);
;                     *(u32x4*)(O + tiled_off(rowi, col0 + bj * HALF, DFF / 64)) = w;
;                 }
.Lpeel_done_141:
	s_lshl_b32 s24, s20, 8
	s_lshl_b32 s5, s21, 8
	s_add_i32 s24, s24, s41
	s_or_b32 s5, s5, s42
	s_and_b32 s22, s24, 0xffffff80
	s_ashr_i32 s5, s5, 6
	s_add_i32 s20, s22, s5
	s_ashr_i32 s21, s20, 31
	v_max_f32_e32 v120, 0, v120
	s_lshl_b64 s[20:21], s[20:21], 14
	v_readlane_b32 s26, v252, 57
	v_or_b32_e32 v136, s24, v132
	v_mul_f32_e32 v140, v120, v120
	v_max_f32_e32 v121, 0, v121
	v_max_f32_e32 v122, 0, v122
	v_readlane_b32 s27, v252, 58
	s_add_u32 s20, s26, s20
	v_lshlrev_b32_e32 v137, 6, v136
	s_movk_i32 s28, 0x3c0
	v_lshlrev_b32_e32 v138, 2, v136
	v_max_f32_e32 v120, 0, v125
	v_mul_f32_e32 v125, v121, v121
	v_max_f32_e32 v121, v126, v126
	v_mul_f32_e32 v126, v122, v122
	s_addc_u32 s21, s27, s21
	s_or_b32 s15, s5, 2
	v_and_or_b32 v137, v137, s28, v133
	v_and_b32_e32 v138, 32, v138
	v_max_f32_e32 v124, 0, v124
	v_mul_f32_e32 v120, v120, v120
	v_max_f32_e32 v121, 0, v121
	v_max_f32_e32 v122, 0, v127
	v_max_f32_e32 v123, 0, v123
	s_add_i32 s22, s15, s22
	v_bitop3_b32 v139, v137, s46, v138 bitop3:0xde
	v_mul_f32_e32 v124, v124, v124
	v_mul_f32_e32 v121, v121, v121
	v_mul_f32_e32 v122, v122, v122
	v_mul_f32_e32 v123, v123, v123
	v_cvt_pk_bf16_f32 v120, v124, v120
	v_max_f32_e32 v112, 0, v112
	v_max_f32_e32 v113, 0, v113
	s_ashr_i32 s23, s22, 31
	v_cvt_pk_bf16_f32 v121, v121, v122
	v_cvt_pk_bf16_f32 v122, v140, v125
	v_cvt_pk_bf16_f32 v123, v126, v123
	global_store_dwordx4 v139, v[120:123], s[20:21] nt
	v_max_f32_e32 v114, 0, v114
	s_lshl_b64 s[22:23], s[22:23], 14
	v_mul_f32_e32 v120, v112, v112
	v_max_f32_e32 v112, v117, v117
	v_mul_f32_e32 v117, v113, v113
	v_max_f32_e32 v112, 0, v112
	v_max_f32_e32 v113, 0, v118
	v_mul_f32_e32 v118, v114, v114
	s_add_u32 s22, s26, s22
	v_max_f32_e32 v116, 0, v116
	v_mul_f32_e32 v112, v112, v112
	v_mul_f32_e32 v113, v113, v113
	v_max_f32_e32 v114, 0, v119
	v_max_f32_e32 v115, 0, v115
	s_addc_u32 s23, s27, s23
	s_or_b32 s25, s24, 16
	v_mul_f32_e32 v116, v116, v116
	v_mul_f32_e32 v114, v114, v114
	v_mul_f32_e32 v115, v115, v115
	v_cvt_pk_bf16_f32 v112, v116, v112
	v_cvt_pk_bf16_f32 v113, v113, v114
	s_lshr_b32 s25, s25, 3
	v_max_f32_e32 v104, 0, v104
	v_cvt_pk_bf16_f32 v114, v120, v117
	v_cvt_pk_bf16_f32 v115, v118, v115
	global_store_dwordx4 v139, v[112:115], s[22:23] nt
	s_and_b32 s25, s25, 10
	v_max_f32_e32 v105, 0, v105
	v_mul_f32_e32 v113, v104, v104
	v_max_f32_e32 v106, 0, v106
	s_or_b32 s25, s25, s45
	v_max_f32_e32 v104, 0, v109
	v_mul_f32_e32 v109, v105, v105
	v_max_f32_e32 v105, v110, v110
	v_mul_f32_e32 v110, v106, v106
	s_lshl_b32 s25, s25, 10
	v_max_f32_e32 v108, 0, v108
	v_mul_f32_e32 v104, v104, v104
	v_max_f32_e32 v105, 0, v105
	v_max_f32_e32 v106, 0, v111
	v_max_f32_e32 v107, 0, v107
	v_bitop3_b32 v112, v137, s25, v138 bitop3:0xde
	v_mul_f32_e32 v108, v108, v108
	v_mul_f32_e32 v105, v105, v105
	v_mul_f32_e32 v106, v106, v106
	v_mul_f32_e32 v107, v107, v107
	v_cvt_pk_bf16_f32 v104, v108, v104
	v_max_f32_e32 v96, 0, v96
	v_max_f32_e32 v97, 0, v97
	v_cvt_pk_bf16_f32 v105, v105, v106
	v_cvt_pk_bf16_f32 v106, v113, v109
	v_cvt_pk_bf16_f32 v107, v110, v107
	global_store_dwordx4 v112, v[104:107], s[20:21] nt
	s_nop 0
	v_max_f32_e32 v98, 0, v98
	v_mul_f32_e32 v104, v96, v96
	v_max_f32_e32 v96, v101, v101
	v_mul_f32_e32 v101, v97, v97
	v_max_f32_e32 v96, 0, v96
	v_max_f32_e32 v97, 0, v102
	v_mul_f32_e32 v102, v98, v98
	v_max_f32_e32 v100, 0, v100
	v_mul_f32_e32 v96, v96, v96
	v_mul_f32_e32 v97, v97, v97
	v_max_f32_e32 v98, 0, v103
	v_max_f32_e32 v99, 0, v99
	s_or_b32 s25, s24, 32
	v_mul_f32_e32 v100, v100, v100
	v_mul_f32_e32 v98, v98, v98
	v_mul_f32_e32 v99, v99, v99
	v_cvt_pk_bf16_f32 v96, v100, v96
	v_cvt_pk_bf16_f32 v97, v97, v98
	s_lshr_b32 s25, s25, 3
	v_max_f32_e32 v88, 0, v88
	v_cvt_pk_bf16_f32 v98, v104, v101
	v_cvt_pk_bf16_f32 v99, v102, v99
	global_store_dwordx4 v112, v[96:99], s[22:23] nt
	s_and_b32 s25, s25, 12
	v_max_f32_e32 v89, 0, v89
	v_mul_f32_e32 v97, v88, v88
	v_max_f32_e32 v90, 0, v90
	s_or_b32 s25, s25, s45
	v_max_f32_e32 v88, 0, v93
	v_mul_f32_e32 v93, v89, v89
	v_max_f32_e32 v89, v94, v94
	v_mul_f32_e32 v94, v90, v90
	s_lshl_b32 s25, s25, 10
	v_max_f32_e32 v92, 0, v92
	v_mul_f32_e32 v88, v88, v88
	v_max_f32_e32 v89, 0, v89
	v_max_f32_e32 v90, 0, v95
	v_max_f32_e32 v91, 0, v91
	v_bitop3_b32 v96, v137, s25, v138 bitop3:0xde
	v_mul_f32_e32 v92, v92, v92
	v_mul_f32_e32 v89, v89, v89
	v_mul_f32_e32 v90, v90, v90
	v_mul_f32_e32 v91, v91, v91
	v_cvt_pk_bf16_f32 v88, v92, v88
	v_max_f32_e32 v80, 0, v80
	v_max_f32_e32 v81, 0, v81
	v_cvt_pk_bf16_f32 v89, v89, v90
	v_cvt_pk_bf16_f32 v90, v97, v93
	v_cvt_pk_bf16_f32 v91, v94, v91
	global_store_dwordx4 v96, v[88:91], s[20:21] nt
	s_nop 0
	v_max_f32_e32 v82, 0, v82
	v_mul_f32_e32 v88, v80, v80
	v_max_f32_e32 v80, v85, v85
	v_mul_f32_e32 v85, v81, v81
	v_max_f32_e32 v80, 0, v80
	v_max_f32_e32 v81, 0, v86
	v_mul_f32_e32 v86, v82, v82
	v_max_f32_e32 v84, 0, v84
	v_mul_f32_e32 v80, v80, v80
	v_mul_f32_e32 v81, v81, v81
	v_max_f32_e32 v82, 0, v87
	v_max_f32_e32 v83, 0, v83
	s_or_b32 s24, s24, 48
	v_mul_f32_e32 v84, v84, v84
	v_mul_f32_e32 v82, v82, v82
	v_mul_f32_e32 v83, v83, v83
	v_cvt_pk_bf16_f32 v80, v84, v80
	v_cvt_pk_bf16_f32 v81, v81, v82
	s_lshr_b32 s24, s24, 3
	v_max_f32_e32 v72, 0, v72
	v_cvt_pk_bf16_f32 v82, v88, v85
	v_cvt_pk_bf16_f32 v83, v86, v83
	global_store_dwordx4 v96, v[80:83], s[22:23] nt
	s_and_b32 s24, s24, 14
	v_max_f32_e32 v73, 0, v73
	v_mul_f32_e32 v81, v72, v72
	v_max_f32_e32 v74, 0, v74
	s_or_b32 s24, s24, s45
	v_max_f32_e32 v72, 0, v77
	v_mul_f32_e32 v77, v73, v73
	v_max_f32_e32 v73, v78, v78
	v_mul_f32_e32 v78, v74, v74
	s_lshl_b32 s24, s24, 10
	v_max_f32_e32 v76, 0, v76
	v_mul_f32_e32 v72, v72, v72
; __device__ __forceinline__ unsigned cvt_pk_bf16(float lo, float hi) { unsigned r; asm volatile("v_cvt_pk_bf16_f32 %0, %1, %2" : "=v"(r) : "v"(lo), "v"(hi)); return r; }
;     __device__ __forceinline__ void operator()(const f32x4 (&acc)[2][2][4][2], const Unit& u, int wr, int wc, int fr, int fq) const {
;     ...
;                 const int rowi = row0 + ai * HALF + m * 16;
; #pragma unroll
;                 for (int bj = 0; bj < 2; ++bj) {
;                     f32x4 v0 = acc[ai][bj][m][0], v1 = acc[ai][bj][m][1];
; #pragma unroll
;                     for (int j = 0; j < 4; ++j) { const float a = fmaxf(v0[j], 0.f), b = fmaxf(v1[j], 0.f); v0[j] = a * a; v1[j] = b * b; }
;                     u32x4 w; w.x = cvt_pk_bf16(v0[0], v0[1]); w.y = cvt_pk_bf16(v0[2], v0[3]); w.z = cvt_pk_bf16(v1[0], v1[1]); w.w = cvt_pk_bf16(v1[2], v1[3]);
;                     *(u32x4*)(O + tiled_off(rowi, col0 + bj * HALF, DFF / 64)) = w;
	v_max_f32_e32 v73, 0, v73
	v_max_f32_e32 v74, 0, v79
	v_max_f32_e32 v75, 0, v75
	v_bitop3_b32 v80, v137, s24, v138 bitop3:0xde
	v_mul_f32_e32 v76, v76, v76
	v_mul_f32_e32 v73, v73, v73
	v_mul_f32_e32 v74, v74, v74
	v_mul_f32_e32 v75, v75, v75
	v_cvt_pk_bf16_f32 v72, v76, v72
	v_max_f32_e32 v64, 0, v64
	v_cvt_pk_bf16_f32 v73, v73, v74
	v_cvt_pk_bf16_f32 v74, v81, v77
	v_cvt_pk_bf16_f32 v75, v78, v75
	global_store_dwordx4 v80, v[72:75], s[20:21] nt
	v_max_f32_e32 v65, 0, v65
	v_max_f32_e32 v66, 0, v66
	v_mul_f32_e32 v72, v64, v64
	v_max_f32_e32 v64, 0, v69
	v_mul_f32_e32 v69, v65, v65
	v_max_f32_e32 v65, v70, v70
	v_mul_f32_e32 v70, v66, v66
	v_max_f32_e32 v68, 0, v68
	v_mul_f32_e32 v64, v64, v64
	v_max_f32_e32 v65, 0, v65
	v_max_f32_e32 v66, 0, v71
	v_max_f32_e32 v67, 0, v67
	v_mul_f32_e32 v68, v68, v68
	v_mul_f32_e32 v65, v65, v65
	v_mul_f32_e32 v66, v66, v66
	v_mul_f32_e32 v67, v67, v67
	v_cvt_pk_bf16_f32 v64, v68, v64
	v_cvt_pk_bf16_f32 v65, v65, v66
	v_cvt_pk_bf16_f32 v66, v72, v69
	v_cvt_pk_bf16_f32 v67, v70, v67
	global_store_dwordx4 v80, v[64:67], s[22:23] nt
	s_nop 0
	v_max_f32_e32 v56, 0, v56
	v_add_u32_e32 v64, 0x80, v136
	v_and_b32_e32 v65, 0xffffff80, v64
	v_lshlrev_b32_e32 v66, 6, v64
	v_lshlrev_b32_e32 v64, 2, v64
	v_and_or_b32 v66, v66, s28, v133
	v_and_b32_e32 v64, 32, v64
	v_bitop3_b32 v152, v66, s46, v64 bitop3:0xde
	v_mul_f32_e32 v64, v56, v56
	v_max_f32_e32 v57, 0, v57
	v_max_f32_e32 v58, 0, v58
	v_max_f32_e32 v60, 0, v60
	v_max_f32_e32 v56, 0, v61
	v_mul_f32_e32 v61, v57, v57
	v_max_f32_e32 v57, v62, v62
	v_mul_f32_e32 v62, v58, v58
	v_mul_f32_e32 v60, v60, v60
	v_mul_f32_e32 v56, v56, v56
	v_max_f32_e32 v57, 0, v57
	v_max_f32_e32 v58, 0, v63
	v_mul_f32_e32 v57, v57, v57
	v_mul_f32_e32 v58, v58, v58
	v_cvt_pk_bf16_f32 v56, v60, v56
	v_add_u32_e32 v60, s5, v65
	v_cvt_pk_bf16_f32 v57, v57, v58
	v_cvt_pk_bf16_f32 v58, v64, v61
	v_ashrrev_i32_e32 v61, 31, v60
	v_max_f32_e32 v59, 0, v59
	v_lshlrev_b64 v[60:61], 14, v[60:61]
	v_mul_f32_e32 v59, v59, v59
	v_lshl_add_u64 v[60:61], s[26:27], 0, v[60:61]
	v_cvt_pk_bf16_f32 v59, v62, v59
	v_lshl_add_u64 v[62:63], v[60:61], 0, v[152:153]
	v_max_f32_e32 v48, 0, v48
	global_store_dwordx4 v[62:63], v[56:59], off nt
	s_nop 0
	v_max_f32_e32 v49, 0, v49
	v_mul_f32_e32 v56, v48, v48
	v_max_f32_e32 v50, 0, v50
	v_max_f32_e32 v52, 0, v52
	v_max_f32_e32 v48, 0, v53
	v_mul_f32_e32 v53, v49, v49
	v_max_f32_e32 v49, v54, v54
	v_mul_f32_e32 v54, v50, v50
	v_mul_f32_e32 v52, v52, v52
	v_mul_f32_e32 v48, v48, v48
	v_max_f32_e32 v49, 0, v49
	v_max_f32_e32 v50, 0, v55
	v_mul_f32_e32 v49, v49, v49
	v_mul_f32_e32 v50, v50, v50
	v_cvt_pk_bf16_f32 v48, v52, v48
	v_add_u32_e32 v52, s15, v65
	v_cvt_pk_bf16_f32 v49, v49, v50
	v_cvt_pk_bf16_f32 v50, v56, v53
	v_ashrrev_i32_e32 v53, 31, v52
	v_max_f32_e32 v51, 0, v51
	v_lshlrev_b64 v[52:53], 14, v[52:53]
	v_mul_f32_e32 v51, v51, v51
	v_lshl_add_u64 v[52:53], s[26:27], 0, v[52:53]
	v_cvt_pk_bf16_f32 v51, v54, v51
	v_lshl_add_u64 v[54:55], v[52:53], 0, v[152:153]
	global_store_dwordx4 v[54:55], v[48:51], off nt
	s_nop 1
	v_add_u32_e32 v48, 0x90, v136
	v_lshrrev_b32_e32 v49, 3, v48
	v_and_or_b32 v49, v49, 10, s45
	v_lshlrev_b32_e32 v50, 6, v48
	v_lshlrev_b32_e32 v48, 2, v48
	v_and_or_b32 v50, v50, s28, v133
	v_lshlrev_b32_e32 v49, 10, v49
	v_and_b32_e32 v48, 32, v48
	v_max_f32_e32 v40, 0, v40
	v_max_f32_e32 v41, 0, v41
	v_max_f32_e32 v42, 0, v42
	v_bitop3_b32 v152, v50, v49, v48 bitop3:0xde
	v_mul_f32_e32 v48, v40, v40
	v_max_f32_e32 v40, v45, v45
	v_mul_f32_e32 v45, v41, v41
	v_max_f32_e32 v41, v46, v46
	v_mul_f32_e32 v46, v42, v42
	v_max_f32_e32 v44, 0, v44
	v_max_f32_e32 v40, 0, v40
	v_max_f32_e32 v41, 0, v41
	v_max_f32_e32 v42, 0, v47
	v_mul_f32_e32 v44, v44, v44
	v_mul_f32_e32 v40, v40, v40
	v_mul_f32_e32 v41, v41, v41
	v_max_f32_e32 v43, 0, v43
	v_mul_f32_e32 v42, v42, v42
	v_mul_f32_e32 v43, v43, v43
	v_cvt_pk_bf16_f32 v40, v44, v40
	v_cvt_pk_bf16_f32 v41, v41, v42
	v_cvt_pk_bf16_f32 v42, v48, v45
	v_lshl_add_u64 v[44:45], v[60:61], 0, v[152:153]
	v_max_f32_e32 v32, 0, v32
	v_max_f32_e32 v33, 0, v33
	v_max_f32_e32 v34, 0, v34
	v_cvt_pk_bf16_f32 v43, v46, v43
	global_store_dwordx4 v[44:45], v[40:43], off nt
	s_nop 0
	v_max_f32_e32 v36, 0, v36
	v_mul_f32_e32 v40, v32, v32
	v_max_f32_e32 v32, v37, v37
	v_mul_f32_e32 v37, v33, v33
; __device__ __forceinline__ unsigned cvt_pk_bf16(float lo, float hi) { unsigned r; asm volatile("v_cvt_pk_bf16_f32 %0, %1, %2" : "=v"(r) : "v"(lo), "v"(hi)); return r; }
; #define PG8_WAIT_V(n) asm volatile("s_waitcnt vmcnt(" #n ")" ::: "memory")
; #define PG8_BAR __builtin_amdgcn_s_barrier()
; template <class Epi>
; __device__ __forceinline__ void gemm_phase(LAS unsigned char* lds, const Gemm g, const StaticOrder& S, const Epi& E) {
;     ...
;         E(acc, cur, wr, wc, fr, fq);
;         if (!has_next) break;
; #pragma unroll
;         for (int a = 0; a < 2; ++a)
; #pragma unroll
;             for (int b = 0; b < 2; ++b)
; #pragma unroll
;                 for (int m = 0; m < 4; ++m)
; #pragma unroll
;                     for (int n = 0; n < 2; ++n) acc[a][b][m][n] = (f32x4){0.f, 0.f, 0.f, 0.f};
;         cur = nxt; cA = nA; cB = nB; ++ui;
;     }
;     PG8_WAIT_V(0);
;     if (wr == 0) PG8_BAR;
;     __device__ __forceinline__ void operator()(const f32x4 (&acc)[2][2][4][2], const Unit& u, int wr, int wc, int fr, int fq) const {
;     ...
;                 const int rowi = row0 + ai * HALF + m * 16;
; #pragma unroll
;                 for (int bj = 0; bj < 2; ++bj) {
;                     f32x4 v0 = acc[ai][bj][m][0], v1 = acc[ai][bj][m][1];
; #pragma unroll
;                     for (int j = 0; j < 4; ++j) { const float a = fmaxf(v0[j], 0.f), b = fmaxf(v1[j], 0.f); v0[j] = a * a; v1[j] = b * b; }
;                     u32x4 w; w.x = cvt_pk_bf16(v0[0], v0[1]); w.y = cvt_pk_bf16(v0[2], v0[3]); w.z = cvt_pk_bf16(v1[0], v1[1]); w.w = cvt_pk_bf16(v1[2], v1[3]);
;                     *(u32x4*)(O + tiled_off(rowi, col0 + bj * HALF, DFF / 64)) = w;
	v_max_f32_e32 v33, v38, v38
	v_mul_f32_e32 v38, v34, v34
	v_max_f32_e32 v32, 0, v32
	v_max_f32_e32 v33, 0, v33
	v_max_f32_e32 v34, 0, v39
	v_mul_f32_e32 v36, v36, v36
	v_mul_f32_e32 v32, v32, v32
	v_mul_f32_e32 v33, v33, v33
	v_max_f32_e32 v35, 0, v35
	v_mul_f32_e32 v34, v34, v34
	v_mul_f32_e32 v35, v35, v35
	v_cvt_pk_bf16_f32 v32, v36, v32
	v_cvt_pk_bf16_f32 v33, v33, v34
	v_cvt_pk_bf16_f32 v34, v40, v37
	v_lshl_add_u64 v[36:37], v[52:53], 0, v[152:153]
	v_cvt_pk_bf16_f32 v35, v38, v35
	global_store_dwordx4 v[36:37], v[32:35], off nt
	s_nop 1
	v_add_u32_e32 v32, 0xa0, v136
	v_lshrrev_b32_e32 v33, 3, v32
	v_and_or_b32 v33, v33, 12, s45
	v_lshlrev_b32_e32 v34, 6, v32
	v_lshlrev_b32_e32 v32, 2, v32
	v_and_or_b32 v34, v34, s28, v133
	v_lshlrev_b32_e32 v33, 10, v33
	v_and_b32_e32 v32, 32, v32
	v_max_f32_e32 v24, 0, v24
	v_max_f32_e32 v25, 0, v25
	v_max_f32_e32 v26, 0, v26
	v_bitop3_b32 v152, v34, v33, v32 bitop3:0xde
	v_mul_f32_e32 v32, v24, v24
	v_max_f32_e32 v24, v29, v29
	v_mul_f32_e32 v29, v25, v25
	v_max_f32_e32 v25, v30, v30
	v_mul_f32_e32 v30, v26, v26
	v_max_f32_e32 v28, 0, v28
	v_max_f32_e32 v24, 0, v24
	v_max_f32_e32 v25, 0, v25
	v_max_f32_e32 v26, 0, v31
	v_mul_f32_e32 v28, v28, v28
	v_mul_f32_e32 v24, v24, v24
	v_mul_f32_e32 v25, v25, v25
	v_max_f32_e32 v27, 0, v27
	v_mul_f32_e32 v26, v26, v26
	v_mul_f32_e32 v27, v27, v27
	v_cvt_pk_bf16_f32 v24, v28, v24
	v_cvt_pk_bf16_f32 v25, v25, v26
	v_cvt_pk_bf16_f32 v26, v32, v29
	v_lshl_add_u64 v[28:29], v[60:61], 0, v[152:153]
	v_max_f32_e32 v16, 0, v16
	v_max_f32_e32 v17, 0, v17
	v_max_f32_e32 v18, 0, v18
	v_cvt_pk_bf16_f32 v27, v30, v27
	global_store_dwordx4 v[28:29], v[24:27], off nt
	s_nop 0
	v_max_f32_e32 v20, 0, v20
	v_mul_f32_e32 v24, v16, v16
	v_max_f32_e32 v16, v21, v21
	v_mul_f32_e32 v21, v17, v17
	v_max_f32_e32 v17, v22, v22
	v_mul_f32_e32 v22, v18, v18
	v_max_f32_e32 v16, 0, v16
	v_max_f32_e32 v17, 0, v17
	v_max_f32_e32 v18, 0, v23
	v_mul_f32_e32 v20, v20, v20
	v_mul_f32_e32 v16, v16, v16
	v_mul_f32_e32 v17, v17, v17
	v_max_f32_e32 v19, 0, v19
	v_mul_f32_e32 v18, v18, v18
	v_mul_f32_e32 v19, v19, v19
	v_cvt_pk_bf16_f32 v16, v20, v16
	v_cvt_pk_bf16_f32 v17, v17, v18
	v_cvt_pk_bf16_f32 v18, v24, v21
	v_lshl_add_u64 v[20:21], v[52:53], 0, v[152:153]
	v_cvt_pk_bf16_f32 v19, v22, v19
	global_store_dwordx4 v[20:21], v[16:19], off nt
	s_nop 1
	v_add_u32_e32 v16, 0xb0, v136
	v_lshrrev_b32_e32 v17, 3, v16
	v_and_or_b32 v17, v17, 14, s45
	v_lshlrev_b32_e32 v18, 6, v16
	v_lshlrev_b32_e32 v16, 2, v16
	v_and_or_b32 v18, v18, s28, v133
	v_lshlrev_b32_e32 v17, 10, v17
	v_and_b32_e32 v16, 32, v16
	v_max_f32_e32 v8, 0, v8
	v_max_f32_e32 v9, 0, v9
	v_max_f32_e32 v10, 0, v10
	v_bitop3_b32 v152, v18, v17, v16 bitop3:0xde
	v_mul_f32_e32 v16, v8, v8
	v_max_f32_e32 v8, v13, v13
	v_mul_f32_e32 v13, v9, v9
	v_max_f32_e32 v9, v14, v14
	v_mul_f32_e32 v14, v10, v10
	v_max_f32_e32 v12, 0, v12
	v_max_f32_e32 v8, 0, v8
	v_max_f32_e32 v9, 0, v9
	v_max_f32_e32 v10, 0, v15
	v_mul_f32_e32 v12, v12, v12
	v_mul_f32_e32 v8, v8, v8
	v_mul_f32_e32 v9, v9, v9
	v_max_f32_e32 v11, 0, v11
	v_mul_f32_e32 v10, v10, v10
	v_mul_f32_e32 v11, v11, v11
	v_cvt_pk_bf16_f32 v8, v12, v8
	v_cvt_pk_bf16_f32 v9, v9, v10
	v_cvt_pk_bf16_f32 v10, v16, v13
	v_lshl_add_u64 v[12:13], v[60:61], 0, v[152:153]
	v_max_f32_e32 v0, 0, v0
	v_max_f32_e32 v1, 0, v1
	v_max_f32_e32 v2, 0, v2
	v_cvt_pk_bf16_f32 v11, v14, v11
	global_store_dwordx4 v[12:13], v[8:11], off nt
	s_nop 0
	v_max_f32_e32 v4, 0, v4
	v_mul_f32_e32 v8, v0, v0
	v_max_f32_e32 v0, v5, v5
	v_mul_f32_e32 v5, v1, v1
	v_max_f32_e32 v1, v6, v6
	v_mul_f32_e32 v6, v2, v2
	v_max_f32_e32 v0, 0, v0
	v_max_f32_e32 v1, 0, v1
	v_max_f32_e32 v2, 0, v7
	v_mul_f32_e32 v4, v4, v4
	v_mul_f32_e32 v0, v0, v0
	v_mul_f32_e32 v1, v1, v1
	v_max_f32_e32 v3, 0, v3
	v_mul_f32_e32 v2, v2, v2
	s_mov_b32 s54, 0xd00ab22c
	v_mul_f32_e32 v3, v3, v3
	v_cvt_pk_bf16_f32 v0, v4, v0
	v_cvt_pk_bf16_f32 v1, v1, v2
	v_cvt_pk_bf16_f32 v2, v8, v5
	v_lshl_add_u64 v[4:5], v[52:53], 0, v[152:153]
	s_and_b64 vcc, exec, s[0:1]
	s_mov_b32 s21, s4
	s_mov_b32 s20, s14
	s_mov_b64 s[24:25], s[18:19]
	s_mov_b64 s[22:23], s[16:17]
	s_mov_b32 s55, 0x3febb5fa
	v_cvt_pk_bf16_f32 v3, v6, v3
	global_store_dwordx4 v[4:5], v[0:3], off nt
	s_cbranch_vccz .LBB0_134
	s_waitcnt vmcnt(0)
	s_cmpk_gt_u32 s31, 0xff
	s_cbranch_scc1 .LBB0_145
	s_barrier
